# norm1 (layer 0) token loop: same chunk-load hoist (row prefetch untouched); stacked on v104
# speedup vs baseline: 1.0105x; 1.0086x over previous
.LBB0_233:
	s_or_b64 exec, exec, s[0:1]
	v_cndmask_b32_e64 v5, v8, 16, s[6:7]
	v_mul_hi_i32_i24_e32 v9, 0x6000, v5
	v_mul_i32_i24_e32 v8, 0x6000, v5
	v_lshl_add_u64 v[8:9], s[12:13], 0, v[8:9]
	v_lshl_add_u64 v[104:105], v[8:9], 0, s[24:25]
	global_load_dwordx4 v[92:95], v[64:65], off
	v_lshl_add_u64 v[10:11], v[104:105], 0, v[60:61]
	global_load_dwordx4 v[96:99], v[10:11], off
	v_lshl_add_u64 v[106:107], v[8:9], 0, v[60:61]
	global_load_dwordx4 v[100:103], v[106:107], off
	global_load_dwordx4 v[120:123], v[64:65], off offset:1024
	v_mov_b32_e32 v156, v72
	v_mov_b32_e32 v157, v61
	v_lshl_add_u64 v[158:159], v[104:105], 0, v[156:157]
	global_load_dwordx4 v[124:127], v[158:159], off
	global_load_dwordx4 v[128:131], v[106:107], off offset:1024
	global_load_dwordx4 v[132:135], v[64:65], off offset:2048
	v_mov_b32_e32 v156, v76
	v_mov_b32_e32 v157, v61
	v_lshl_add_u64 v[158:159], v[104:105], 0, v[156:157]
	global_load_dwordx4 v[136:139], v[158:159], off
	global_load_dwordx4 v[140:143], v[106:107], off offset:2048
	global_load_dwordx4 v[144:147], v[64:65], off offset:3072
	v_mov_b32_e32 v156, v80
	v_mov_b32_e32 v157, v61
	v_lshl_add_u64 v[158:159], v[104:105], 0, v[156:157]
	global_load_dwordx4 v[148:151], v[158:159], off
	global_load_dwordx4 v[152:155], v[106:107], off offset:3072
	s_waitcnt vmcnt(0) lgkmcnt(0)
	v_mov_b32_e32 v108, v0
	v_mov_b32_e32 v8, v0
	v_mov_b32_e32 v110, v1
	v_mov_b32_e32 v0, v1
	v_mov_b32_e32 v1, v57
	v_ashrrev_i32_e32 v5, 31, v4
	v_mov_b32_e32 v9, v56
	v_mov_b32_e32 v18, v53
	v_mov_b32_e32 v19, v49
	v_pk_mul_f32 v[0:1], v[0:1], v[0:1]
	v_mov_b32_e32 v10, v2
	v_mov_b32_e32 v11, v58
	v_mov_b32_e32 v16, v52
	v_mov_b32_e32 v17, v48
	v_lshlrev_b64 v[4:5], 12, v[4:5]
	v_pk_mul_f32 v[18:19], v[18:19], v[18:19]
	v_pk_fma_f32 v[0:1], v[8:9], v[8:9], v[0:1]
	v_mov_b32_e32 v109, v2
	v_mov_b32_e32 v111, v3
	v_mov_b32_e32 v2, v3
	v_mov_b32_e32 v3, v59
	v_mov_b32_e32 v112, v54
	v_mov_b32_e32 v113, v50
	v_lshl_add_u64 v[4:5], v[6:7], 0, v[4:5]
	v_pk_fma_f32 v[6:7], v[16:17], v[16:17], v[18:19]
	v_pk_fma_f32 v[0:1], v[10:11], v[10:11], v[0:1]
	v_mov_b32_e32 v114, v55
	v_mov_b32_e32 v115, v51
	v_lshl_add_u64 v[116:117], v[4:5], 0, v[60:61]
	v_pk_fma_f32 v[4:5], v[112:113], v[112:113], v[6:7]
	v_pk_fma_f32 v[0:1], v[2:3], v[2:3], v[0:1]
	v_pk_fma_f32 v[2:3], v[114:115], v[114:115], v[4:5]
	v_add_f32_e32 v0, v0, v1
	v_add_f32_e32 v0, v0, v2
	v_add_f32_e32 v0, v0, v3
	v_mov_b32_e32 v114, v92
	s_nop 0
	v_add_f32_dpp v0, v0, v0 quad_perm:[1,0,3,2] row_mask:0xf bank_mask:0xf bound_ctrl:1
	v_mov_b32_e32 v115, v94
	v_mov_b32_e32 v94, v93
	v_add_f32_dpp v0, v0, v0 quad_perm:[2,3,0,1] row_mask:0xf bank_mask:0xf bound_ctrl:1
	s_nop 1
	v_add_f32_dpp v0, v0, v0 row_half_mirror row_mask:0xf bank_mask:0xf bound_ctrl:1
	s_nop 1
	v_add_f32_dpp v0, v0, v0 row_mirror row_mask:0xf bank_mask:0xf bound_ctrl:1
	s_nop 0
	v_readlane_b32 s6, v0, 16
	v_readlane_b32 s7, v0, 48
	v_readlane_b32 s0, v0, 0
	v_readlane_b32 s1, v0, 32
	v_mov_b32_e32 v0, s6
	v_mov_b32_e32 v1, s7
	v_pk_add_f32 v[0:1], s[0:1], v[0:1]
	s_nop 0
	v_add_f32_e32 v0, v0, v1
	v_fmamk_f32 v0, v0, 0x3a800000, v88
	v_mul_f32_e32 v1, 0x4b800000, v0
	v_cmp_gt_f32_e64 s[0:1], s48, v0
	s_nop 1
	v_cndmask_b32_e64 v0, v0, v1, s[0:1]
	v_rsq_f32_e32 v79, v0
	global_load_dwordx4 v[16:19], v[116:117], off
	global_load_dwordx4 v[8:11], v[116:117], off offset:1024
	global_load_dwordx4 v[4:7], v[116:117], off offset:2048
	global_load_dwordx4 v[0:3], v[116:117], off offset:3072
	v_mul_f32_e32 v87, 0x45800000, v79
	v_cndmask_b32_e64 v112, v79, v87, s[0:1]
	v_pk_mul_f32 v[108:109], v[108:109], v[112:113] op_sel_hi:[1,0]
	v_pk_mul_f32 v[110:111], v[110:111], v[112:113] op_sel_hi:[1,0]
	v_pk_mul_f32 v[92:93], v[114:115], v[108:109]
	v_mov_b32_e32 v108, v96
	v_mov_b32_e32 v109, v98
	v_pk_mul_f32 v[94:95], v[94:95], v[110:111]
	v_mov_b32_e32 v110, v100
	v_mov_b32_e32 v111, v102
	v_mov_b32_e32 v98, v97
	v_pk_add_f32 v[96:97], v[108:109], 1.0 op_sel_hi:[1,0]
	v_mov_b32_e32 v102, v101
	v_pk_add_f32 v[98:99], v[98:99], 1.0 op_sel_hi:[1,0]
	v_pk_fma_f32 v[92:93], v[96:97], v[92:93], v[110:111]
	v_pk_fma_f32 v[94:95], v[98:99], v[94:95], v[102:103]
	v_and_b32_sdwa v87, v92, v89 dst_sel:DWORD dst_unused:UNUSED_PAD src0_sel:WORD_1 src1_sel:DWORD
	v_and_b32_sdwa v91, v95, v89 dst_sel:DWORD dst_unused:UNUSED_PAD src0_sel:WORD_1 src1_sel:DWORD
	v_add3_u32 v87, v92, v87, s49
	v_and_b32_sdwa v92, v94, v89 dst_sel:DWORD dst_unused:UNUSED_PAD src0_sel:WORD_1 src1_sel:DWORD
	v_and_b32_sdwa v79, v93, v89 dst_sel:DWORD dst_unused:UNUSED_PAD src0_sel:WORD_1 src1_sel:DWORD
	v_add3_u32 v91, v95, v91, s49
	v_add3_u32 v92, v94, v92, s49
	v_add3_u32 v79, v93, v79, s49
	v_and_b32_e32 v91, 0xffff0000, v91
	v_and_b32_e32 v92, 0xffff0000, v92
	v_or_b32_sdwa v93, v91, v79 dst_sel:DWORD dst_unused:UNUSED_PAD src0_sel:DWORD src1_sel:WORD_1
	v_or_b32_sdwa v92, v92, v87 dst_sel:DWORD dst_unused:UNUSED_PAD src0_sel:DWORD src1_sel:WORD_1
	global_store_dwordx2 v[68:69], v[92:93], off
	v_lshl_add_u64 v[96:97], v[104:105], 0, v[72:73]
	s_nop 0
	v_mov_b32_e32 v108, v56
	v_mov_b32_e32 v109, v58
	v_mov_b32_e32 v58, v57
	v_pk_mul_f32 v[56:57], v[108:109], v[112:113] op_sel_hi:[1,0]
	v_pk_mul_f32 v[58:59], v[58:59], v[112:113] op_sel_hi:[1,0]
	v_cmp_gt_i32_e64 s[0:1], s41, v75
	s_waitcnt lgkmcnt(0)
	v_mov_b32_e32 v92, v120
	v_mov_b32_e32 v93, v121
	v_mov_b32_e32 v94, v122
	v_mov_b32_e32 v95, v123
	v_mov_b32_e32 v96, v124
	v_mov_b32_e32 v97, v125
	v_mov_b32_e32 v98, v126
	v_mov_b32_e32 v99, v127
	v_mov_b32_e32 v100, v128
	v_mov_b32_e32 v101, v129
	v_mov_b32_e32 v102, v130
	v_mov_b32_e32 v103, v131
	v_mov_b32_e32 v109, v94
	v_mov_b32_e32 v111, v98
	v_mov_b32_e32 v94, v93
	v_mov_b32_e32 v98, v97
	v_mov_b32_e32 v108, v92
	v_mov_b32_e32 v110, v96
	v_mov_b32_e32 v115, v102
	v_mov_b32_e32 v102, v101
	v_pk_mul_f32 v[58:59], v[58:59], v[94:95]
	v_pk_add_f32 v[94:95], v[98:99], 1.0 op_sel_hi:[1,0]
	v_mov_b32_e32 v114, v100
	v_pk_mul_f32 v[56:57], v[56:57], v[108:109]
	v_pk_add_f32 v[92:93], v[110:111], 1.0 op_sel_hi:[1,0]
	v_pk_fma_f32 v[58:59], v[58:59], v[94:95], v[102:103]
	v_pk_fma_f32 v[56:57], v[56:57], v[92:93], v[114:115]
	v_and_b32_sdwa v91, v59, v89 dst_sel:DWORD dst_unused:UNUSED_PAD src0_sel:WORD_1 src1_sel:DWORD
	v_and_b32_sdwa v92, v58, v89 dst_sel:DWORD dst_unused:UNUSED_PAD src0_sel:WORD_1 src1_sel:DWORD
	v_and_b32_sdwa v79, v57, v89 dst_sel:DWORD dst_unused:UNUSED_PAD src0_sel:WORD_1 src1_sel:DWORD
	v_and_b32_sdwa v87, v56, v89 dst_sel:DWORD dst_unused:UNUSED_PAD src0_sel:WORD_1 src1_sel:DWORD
	v_add3_u32 v59, v59, v91, s49
	v_add3_u32 v58, v58, v92, s49
	v_add3_u32 v56, v56, v87, s49
	v_add3_u32 v57, v57, v79, s49
	v_and_b32_e32 v59, 0xffff0000, v59
	v_and_b32_e32 v58, 0xffff0000, v58
	v_or_b32_sdwa v57, v59, v57 dst_sel:DWORD dst_unused:UNUSED_PAD src0_sel:DWORD src1_sel:WORD_1
	v_or_b32_sdwa v56, v58, v56 dst_sel:DWORD dst_unused:UNUSED_PAD src0_sel:DWORD src1_sel:WORD_1
	global_store_dwordx2 v[68:69], v[56:57], off offset:512
	v_lshl_add_u64 v[92:93], v[104:105], 0, v[76:77]
	s_nop 0
	v_mov_b32_e32 v100, v52
	v_mov_b32_e32 v101, v54
	v_mov_b32_e32 v54, v53
	v_pk_mul_f32 v[52:53], v[100:101], v[112:113] op_sel_hi:[1,0]
	v_pk_mul_f32 v[54:55], v[54:55], v[112:113] op_sel_hi:[1,0]
	s_waitcnt lgkmcnt(0)
	v_mov_b32_e32 v56, v132
	v_mov_b32_e32 v57, v133
	v_mov_b32_e32 v58, v134
	v_mov_b32_e32 v59, v135
	v_mov_b32_e32 v92, v136
	v_mov_b32_e32 v93, v137
	v_mov_b32_e32 v94, v138
	v_mov_b32_e32 v95, v139
	v_mov_b32_e32 v96, v140
	v_mov_b32_e32 v97, v141
	v_mov_b32_e32 v98, v142
	v_mov_b32_e32 v99, v143
	v_mov_b32_e32 v101, v58
	v_mov_b32_e32 v103, v94
	v_mov_b32_e32 v58, v57
	v_mov_b32_e32 v94, v93
	v_mov_b32_e32 v100, v56
	v_mov_b32_e32 v102, v92
	v_mov_b32_e32 v109, v98
	v_mov_b32_e32 v98, v97
	v_pk_mul_f32 v[54:55], v[54:55], v[58:59]
	v_pk_add_f32 v[58:59], v[94:95], 1.0 op_sel_hi:[1,0]
	v_mov_b32_e32 v108, v96
	v_pk_mul_f32 v[52:53], v[52:53], v[100:101]
	v_pk_add_f32 v[56:57], v[102:103], 1.0 op_sel_hi:[1,0]
	v_pk_fma_f32 v[54:55], v[54:55], v[58:59], v[98:99]
	v_pk_fma_f32 v[52:53], v[52:53], v[56:57], v[108:109]
	v_and_b32_sdwa v58, v55, v89 dst_sel:DWORD dst_unused:UNUSED_PAD src0_sel:WORD_1 src1_sel:DWORD
	v_and_b32_sdwa v59, v54, v89 dst_sel:DWORD dst_unused:UNUSED_PAD src0_sel:WORD_1 src1_sel:DWORD
	v_and_b32_sdwa v56, v53, v89 dst_sel:DWORD dst_unused:UNUSED_PAD src0_sel:WORD_1 src1_sel:DWORD
	v_and_b32_sdwa v57, v52, v89 dst_sel:DWORD dst_unused:UNUSED_PAD src0_sel:WORD_1 src1_sel:DWORD
	v_add3_u32 v55, v55, v58, s49
	v_add3_u32 v54, v54, v59, s49
	v_add3_u32 v52, v52, v57, s49
	v_add3_u32 v53, v53, v56, s49
	v_and_b32_e32 v55, 0xffff0000, v55
	v_and_b32_e32 v54, 0xffff0000, v54
	v_or_b32_sdwa v53, v55, v53 dst_sel:DWORD dst_unused:UNUSED_PAD src0_sel:DWORD src1_sel:WORD_1
	v_or_b32_sdwa v52, v54, v52 dst_sel:DWORD dst_unused:UNUSED_PAD src0_sel:DWORD src1_sel:WORD_1
	global_store_dwordx2 v[68:69], v[52:53], off offset:1024
	v_lshl_add_u64 v[56:57], v[104:105], 0, v[80:81]
	s_nop 0
	v_mov_b32_e32 v96, v48
	v_mov_b32_e32 v97, v50
	v_mov_b32_e32 v50, v49
	v_pk_mul_f32 v[48:49], v[96:97], v[112:113] op_sel_hi:[1,0]
	v_pk_mul_f32 v[50:51], v[50:51], v[112:113] op_sel_hi:[1,0]
	s_waitcnt lgkmcnt(0)
	v_mov_b32_e32 v52, v144
	v_mov_b32_e32 v53, v145
	v_mov_b32_e32 v54, v146
	v_mov_b32_e32 v55, v147
	v_mov_b32_e32 v56, v148
	v_mov_b32_e32 v57, v149
	v_mov_b32_e32 v58, v150
	v_mov_b32_e32 v59, v151
	v_mov_b32_e32 v92, v152
	v_mov_b32_e32 v93, v153
	v_mov_b32_e32 v94, v154
	v_mov_b32_e32 v95, v155
	v_mov_b32_e32 v97, v54
	v_mov_b32_e32 v99, v58
	v_mov_b32_e32 v54, v53
	v_mov_b32_e32 v58, v57
	v_mov_b32_e32 v96, v52
	v_mov_b32_e32 v98, v56
	v_mov_b32_e32 v101, v94
	v_mov_b32_e32 v94, v93
	v_pk_mul_f32 v[50:51], v[50:51], v[54:55]
	v_pk_add_f32 v[54:55], v[58:59], 1.0 op_sel_hi:[1,0]
	v_mov_b32_e32 v100, v92
	v_pk_mul_f32 v[48:49], v[48:49], v[96:97]
	v_pk_add_f32 v[52:53], v[98:99], 1.0 op_sel_hi:[1,0]
	v_pk_fma_f32 v[50:51], v[50:51], v[54:55], v[94:95]
	v_pk_fma_f32 v[48:49], v[48:49], v[52:53], v[100:101]
	v_and_b32_sdwa v54, v51, v89 dst_sel:DWORD dst_unused:UNUSED_PAD src0_sel:WORD_1 src1_sel:DWORD
	v_and_b32_sdwa v55, v50, v89 dst_sel:DWORD dst_unused:UNUSED_PAD src0_sel:WORD_1 src1_sel:DWORD
	v_and_b32_sdwa v52, v49, v89 dst_sel:DWORD dst_unused:UNUSED_PAD src0_sel:WORD_1 src1_sel:DWORD
	v_and_b32_sdwa v53, v48, v89 dst_sel:DWORD dst_unused:UNUSED_PAD src0_sel:WORD_1 src1_sel:DWORD
	v_add3_u32 v51, v51, v54, s49
	v_add3_u32 v50, v50, v55, s49
	v_add3_u32 v48, v48, v53, s49
	v_add3_u32 v49, v49, v52, s49
	v_and_b32_e32 v51, 0xffff0000, v51
	v_and_b32_e32 v50, 0xffff0000, v50
	v_or_b32_sdwa v49, v51, v49 dst_sel:DWORD dst_unused:UNUSED_PAD src0_sel:DWORD src1_sel:WORD_1
	v_or_b32_sdwa v48, v50, v48 dst_sel:DWORD dst_unused:UNUSED_PAD src0_sel:DWORD src1_sel:WORD_1
	global_store_dwordx2 v[68:69], v[48:49], off offset:1536
	s_and_saveexec_b64 s[6:7], s[0:1]
	s_cbranch_execz .LBB0_216
	v_cndmask_b32_e64 v48, v71, 16, s[4:5]
	v_mul_hi_i32_i24_e32 v49, 0x6000, v48
	v_mul_i32_i24_e32 v48, 0x6000, v48
	v_lshl_add_u64 v[50:51], s[12:13], 0, v[48:49]
	v_lshl_add_u64 v[48:49], v[50:51], 0, s[24:25]
	global_load_dwordx4 v[52:55], v[64:65], off
	v_lshl_add_u64 v[56:57], v[48:49], 0, v[60:61]
	global_load_dwordx4 v[56:59], v[56:57], off
	v_lshl_add_u64 v[50:51], v[50:51], 0, v[60:61]
	global_load_dwordx4 v[92:95], v[50:51], off
	global_load_dwordx4 v[120:123], v[64:65], off offset:1024
	v_mov_b32_e32 v156, v70
	v_mov_b32_e32 v157, v61
	v_lshl_add_u64 v[158:159], v[48:49], 0, v[156:157]
	global_load_dwordx4 v[124:127], v[158:159], off
	global_load_dwordx4 v[128:131], v[50:51], off offset:1024
	global_load_dwordx4 v[132:135], v[64:65], off offset:2048
	v_mov_b32_e32 v156, v74
	v_mov_b32_e32 v157, v61
	v_lshl_add_u64 v[158:159], v[48:49], 0, v[156:157]
	global_load_dwordx4 v[136:139], v[158:159], off
	global_load_dwordx4 v[140:143], v[50:51], off offset:2048
	global_load_dwordx4 v[144:147], v[64:65], off offset:3072
	v_mov_b32_e32 v156, v78
	v_mov_b32_e32 v157, v61
	v_lshl_add_u64 v[158:159], v[48:49], 0, v[156:157]
	global_load_dwordx4 v[148:151], v[158:159], off
	global_load_dwordx4 v[152:155], v[50:51], off offset:3072
	v_mov_b32_e32 v96, v44
	v_mov_b32_e32 v98, v44
	v_mov_b32_e32 v100, v45
	v_mov_b32_e32 v44, v45
	v_mov_b32_e32 v45, v41
	v_mov_b32_e32 v99, v40
	v_mov_b32_e32 v106, v37
	v_mov_b32_e32 v107, v33
	v_pk_mul_f32 v[44:45], v[44:45], v[44:45]
	v_mov_b32_e32 v102, v46
	v_mov_b32_e32 v103, v42
	v_mov_b32_e32 v104, v36
	v_mov_b32_e32 v105, v32
	v_pk_mul_f32 v[106:107], v[106:107], v[106:107]
	v_pk_fma_f32 v[44:45], v[98:99], v[98:99], v[44:45]
	v_mov_b32_e32 v97, v46
	v_mov_b32_e32 v101, v47
	v_mov_b32_e32 v46, v47
	v_mov_b32_e32 v47, v43
	v_mov_b32_e32 v108, v38
	v_mov_b32_e32 v109, v34
	v_pk_fma_f32 v[98:99], v[104:105], v[104:105], v[106:107]
	v_pk_fma_f32 v[44:45], v[102:103], v[102:103], v[44:45]
	v_mov_b32_e32 v110, v39
	v_mov_b32_e32 v111, v35
	v_pk_fma_f32 v[98:99], v[108:109], v[108:109], v[98:99]
	v_pk_fma_f32 v[44:45], v[46:47], v[46:47], v[44:45]
	v_pk_fma_f32 v[46:47], v[110:111], v[110:111], v[98:99]
	v_add_f32_e32 v44, v44, v45
	v_add_f32_e32 v44, v44, v46
	v_add_f32_e32 v44, v44, v47
	v_ashrrev_i32_e32 v87, 31, v86
	v_mov_b32_e32 v71, v61
	v_add_f32_dpp v44, v44, v44 quad_perm:[1,0,3,2] row_mask:0xf bank_mask:0xf bound_ctrl:1
	v_mov_b32_e32 v75, v61
	v_mov_b32_e32 v79, v61
	v_add_f32_dpp v44, v44, v44 quad_perm:[2,3,0,1] row_mask:0xf bank_mask:0xf bound_ctrl:1
	s_waitcnt vmcnt(0) lgkmcnt(0)
	v_mov_b32_e32 v99, v54
	v_add_f32_dpp v44, v44, v44 row_half_mirror row_mask:0xf bank_mask:0xf bound_ctrl:1
	v_mov_b32_e32 v54, v53
	v_mov_b32_e32 v98, v52
	v_add_f32_dpp v44, v44, v44 row_mirror row_mask:0xf bank_mask:0xf bound_ctrl:1
	s_nop 0
	v_readlane_b32 s4, v44, 16
	v_readlane_b32 s5, v44, 48
	v_readlane_b32 s0, v44, 0
	v_readlane_b32 s1, v44, 32
	v_mov_b32_e32 v44, s4
	v_mov_b32_e32 v45, s5
	v_pk_add_f32 v[44:45], s[0:1], v[44:45]
	s_nop 0
	v_add_f32_e32 v44, v44, v45
	v_fmamk_f32 v44, v44, 0x3a800000, v88
	v_mul_f32_e32 v45, 0x4b800000, v44
	v_cmp_gt_f32_e64 s[0:1], s48, v44
	s_nop 1
	v_cndmask_b32_e64 v44, v44, v45, s[0:1]
	v_rsq_f32_e32 v46, v44
	v_lshlrev_b64 v[44:45], 11, v[86:87]
	v_lshl_add_u64 v[44:45], v[66:67], 0, v[44:45]
	v_mul_f32_e32 v47, 0x45800000, v46
	v_cndmask_b32_e64 v86, v46, v47, s[0:1]
	v_pk_mul_f32 v[46:47], v[96:97], v[86:87] op_sel_hi:[1,0]
	v_pk_mul_f32 v[96:97], v[100:101], v[86:87] op_sel_hi:[1,0]
	v_pk_mul_f32 v[46:47], v[98:99], v[46:47]
	v_pk_mul_f32 v[52:53], v[54:55], v[96:97]
	v_mov_b32_e32 v55, v58
	v_mov_b32_e32 v58, v57
	v_mov_b32_e32 v54, v56
	v_mov_b32_e32 v97, v94
	v_mov_b32_e32 v94, v93
	v_pk_add_f32 v[56:57], v[58:59], 1.0 op_sel_hi:[1,0]
	v_mov_b32_e32 v96, v92
	v_pk_add_f32 v[54:55], v[54:55], 1.0 op_sel_hi:[1,0]
	v_pk_fma_f32 v[52:53], v[56:57], v[52:53], v[94:95]
	v_pk_fma_f32 v[46:47], v[54:55], v[46:47], v[96:97]
	v_and_b32_sdwa v56, v53, v89 dst_sel:DWORD dst_unused:UNUSED_PAD src0_sel:WORD_1 src1_sel:DWORD
	v_and_b32_sdwa v57, v52, v89 dst_sel:DWORD dst_unused:UNUSED_PAD src0_sel:WORD_1 src1_sel:DWORD
	v_and_b32_sdwa v54, v47, v89 dst_sel:DWORD dst_unused:UNUSED_PAD src0_sel:WORD_1 src1_sel:DWORD
	v_and_b32_sdwa v55, v46, v89 dst_sel:DWORD dst_unused:UNUSED_PAD src0_sel:WORD_1 src1_sel:DWORD
	v_add3_u32 v53, v53, v56, s49
	v_add3_u32 v52, v52, v57, s49
	v_add3_u32 v46, v46, v55, s49
	v_add3_u32 v47, v47, v54, s49
	v_and_b32_e32 v53, 0xffff0000, v53
	v_and_b32_e32 v52, 0xffff0000, v52
	v_or_b32_sdwa v47, v53, v47 dst_sel:DWORD dst_unused:UNUSED_PAD src0_sel:DWORD src1_sel:WORD_1
	v_or_b32_sdwa v46, v52, v46 dst_sel:DWORD dst_unused:UNUSED_PAD src0_sel:DWORD src1_sel:WORD_1
	global_store_dwordx2 v[44:45], v[46:47], off
	v_lshl_add_u64 v[46:47], v[48:49], 0, v[70:71]
	v_mov_b32_e32 v46, v40
	v_mov_b32_e32 v47, v42
	v_mov_b32_e32 v42, v41
	v_pk_mul_f32 v[40:41], v[46:47], v[86:87] op_sel_hi:[1,0]
	v_pk_mul_f32 v[42:43], v[42:43], v[86:87] op_sel_hi:[1,0]
	v_cmp_gt_i32_e64 s[0:1], s41, v90
	s_waitcnt lgkmcnt(0)
	v_mov_b32_e32 v52, v120
	v_mov_b32_e32 v53, v121
	v_mov_b32_e32 v54, v122
	v_mov_b32_e32 v55, v123
	v_mov_b32_e32 v56, v124
	v_mov_b32_e32 v57, v125
	v_mov_b32_e32 v58, v126
	v_mov_b32_e32 v59, v127
	v_mov_b32_e32 v92, v128
	v_mov_b32_e32 v93, v129
	v_mov_b32_e32 v94, v130
	v_mov_b32_e32 v95, v131
	v_mov_b32_e32 v47, v54
	v_mov_b32_e32 v97, v58
	v_mov_b32_e32 v54, v53
	v_mov_b32_e32 v58, v57
	v_mov_b32_e32 v46, v52
	v_mov_b32_e32 v96, v56
	v_mov_b32_e32 v99, v94
	v_mov_b32_e32 v94, v93
	v_pk_mul_f32 v[42:43], v[42:43], v[54:55]
	v_pk_add_f32 v[52:53], v[58:59], 1.0 op_sel_hi:[1,0]
	v_mov_b32_e32 v98, v92
	v_pk_mul_f32 v[40:41], v[40:41], v[46:47]
	v_pk_add_f32 v[46:47], v[96:97], 1.0 op_sel_hi:[1,0]
	v_pk_fma_f32 v[42:43], v[42:43], v[52:53], v[94:95]
	v_pk_fma_f32 v[40:41], v[40:41], v[46:47], v[98:99]
	v_and_b32_sdwa v52, v43, v89 dst_sel:DWORD dst_unused:UNUSED_PAD src0_sel:WORD_1 src1_sel:DWORD
	v_and_b32_sdwa v53, v42, v89 dst_sel:DWORD dst_unused:UNUSED_PAD src0_sel:WORD_1 src1_sel:DWORD
	v_and_b32_sdwa v46, v41, v89 dst_sel:DWORD dst_unused:UNUSED_PAD src0_sel:WORD_1 src1_sel:DWORD
	v_and_b32_sdwa v47, v40, v89 dst_sel:DWORD dst_unused:UNUSED_PAD src0_sel:WORD_1 src1_sel:DWORD
	v_add3_u32 v43, v43, v52, s49
	v_add3_u32 v42, v42, v53, s49
	v_add3_u32 v40, v40, v47, s49
	v_add3_u32 v41, v41, v46, s49
	v_and_b32_e32 v43, 0xffff0000, v43
	v_and_b32_e32 v42, 0xffff0000, v42
	v_or_b32_sdwa v41, v43, v41 dst_sel:DWORD dst_unused:UNUSED_PAD src0_sel:DWORD src1_sel:WORD_1
	v_or_b32_sdwa v40, v42, v40 dst_sel:DWORD dst_unused:UNUSED_PAD src0_sel:DWORD src1_sel:WORD_1
	global_store_dwordx2 v[44:45], v[40:41], off offset:512
	v_lshl_add_u64 v[46:47], v[48:49], 0, v[74:75]
	v_mov_b32_e32 v46, v36
	v_mov_b32_e32 v47, v38
	v_mov_b32_e32 v38, v37
	v_pk_mul_f32 v[36:37], v[46:47], v[86:87] op_sel_hi:[1,0]
	v_pk_mul_f32 v[38:39], v[38:39], v[86:87] op_sel_hi:[1,0]
	s_waitcnt lgkmcnt(0)
	v_mov_b32_e32 v40, v132
	v_mov_b32_e32 v41, v133
	v_mov_b32_e32 v42, v134
	v_mov_b32_e32 v43, v135
	v_mov_b32_e32 v52, v136
	v_mov_b32_e32 v53, v137
	v_mov_b32_e32 v54, v138
	v_mov_b32_e32 v55, v139
	v_mov_b32_e32 v56, v140
	v_mov_b32_e32 v57, v141
	v_mov_b32_e32 v58, v142
	v_mov_b32_e32 v59, v143
	v_mov_b32_e32 v47, v42
	v_mov_b32_e32 v93, v54
	v_mov_b32_e32 v42, v41
	v_mov_b32_e32 v54, v53
	v_mov_b32_e32 v46, v40
	v_mov_b32_e32 v92, v52
	v_mov_b32_e32 v95, v58
	v_mov_b32_e32 v58, v57
	v_pk_mul_f32 v[38:39], v[38:39], v[42:43]
	v_pk_add_f32 v[42:43], v[54:55], 1.0 op_sel_hi:[1,0]
	v_mov_b32_e32 v94, v56
	v_pk_mul_f32 v[36:37], v[36:37], v[46:47]
	v_pk_add_f32 v[40:41], v[92:93], 1.0 op_sel_hi:[1,0]
	v_pk_fma_f32 v[38:39], v[38:39], v[42:43], v[58:59]
	v_pk_fma_f32 v[36:37], v[36:37], v[40:41], v[94:95]
	v_and_b32_sdwa v42, v39, v89 dst_sel:DWORD dst_unused:UNUSED_PAD src0_sel:WORD_1 src1_sel:DWORD
	v_and_b32_sdwa v43, v38, v89 dst_sel:DWORD dst_unused:UNUSED_PAD src0_sel:WORD_1 src1_sel:DWORD
	v_and_b32_sdwa v40, v37, v89 dst_sel:DWORD dst_unused:UNUSED_PAD src0_sel:WORD_1 src1_sel:DWORD
	v_and_b32_sdwa v41, v36, v89 dst_sel:DWORD dst_unused:UNUSED_PAD src0_sel:WORD_1 src1_sel:DWORD
	v_add3_u32 v39, v39, v42, s49
	v_add3_u32 v38, v38, v43, s49
	v_add3_u32 v36, v36, v41, s49
	v_add3_u32 v37, v37, v40, s49
	v_and_b32_e32 v39, 0xffff0000, v39
	v_and_b32_e32 v38, 0xffff0000, v38
	v_or_b32_sdwa v37, v39, v37 dst_sel:DWORD dst_unused:UNUSED_PAD src0_sel:DWORD src1_sel:WORD_1
	v_or_b32_sdwa v36, v38, v36 dst_sel:DWORD dst_unused:UNUSED_PAD src0_sel:DWORD src1_sel:WORD_1
	global_store_dwordx2 v[44:45], v[36:37], off offset:1024
	v_lshl_add_u64 v[40:41], v[48:49], 0, v[78:79]
	s_nop 0
	v_mov_b32_e32 v50, v32
	v_mov_b32_e32 v51, v34
	v_mov_b32_e32 v34, v33
	v_pk_mul_f32 v[32:33], v[50:51], v[86:87] op_sel_hi:[1,0]
	v_pk_mul_f32 v[34:35], v[34:35], v[86:87] op_sel_hi:[1,0]
	s_waitcnt lgkmcnt(0)
	v_mov_b32_e32 v36, v144
	v_mov_b32_e32 v37, v145
	v_mov_b32_e32 v38, v146
	v_mov_b32_e32 v39, v147
	v_mov_b32_e32 v40, v148
	v_mov_b32_e32 v41, v149
	v_mov_b32_e32 v42, v150
	v_mov_b32_e32 v43, v151
	v_mov_b32_e32 v46, v152
	v_mov_b32_e32 v47, v153
	v_mov_b32_e32 v48, v154
	v_mov_b32_e32 v49, v155
	v_mov_b32_e32 v51, v38
	v_mov_b32_e32 v53, v42
	v_mov_b32_e32 v38, v37
	v_mov_b32_e32 v42, v41
	v_mov_b32_e32 v50, v36
	v_mov_b32_e32 v52, v40
	v_mov_b32_e32 v55, v48
	v_mov_b32_e32 v48, v47
	v_pk_mul_f32 v[34:35], v[34:35], v[38:39]
	v_pk_add_f32 v[38:39], v[42:43], 1.0 op_sel_hi:[1,0]
	v_mov_b32_e32 v54, v46
	v_pk_mul_f32 v[32:33], v[32:33], v[50:51]
	v_pk_add_f32 v[36:37], v[52:53], 1.0 op_sel_hi:[1,0]
	v_pk_fma_f32 v[34:35], v[34:35], v[38:39], v[48:49]
	v_pk_fma_f32 v[32:33], v[32:33], v[36:37], v[54:55]
	v_and_b32_sdwa v38, v35, v89 dst_sel:DWORD dst_unused:UNUSED_PAD src0_sel:WORD_1 src1_sel:DWORD
	v_and_b32_sdwa v39, v34, v89 dst_sel:DWORD dst_unused:UNUSED_PAD src0_sel:WORD_1 src1_sel:DWORD
	v_and_b32_sdwa v36, v33, v89 dst_sel:DWORD dst_unused:UNUSED_PAD src0_sel:WORD_1 src1_sel:DWORD
	v_and_b32_sdwa v37, v32, v89 dst_sel:DWORD dst_unused:UNUSED_PAD src0_sel:WORD_1 src1_sel:DWORD
	v_add3_u32 v35, v35, v38, s49
	v_add3_u32 v34, v34, v39, s49
	v_add3_u32 v32, v32, v37, s49
	v_add3_u32 v33, v33, v36, s49
	v_and_b32_e32 v35, 0xffff0000, v35
	v_and_b32_e32 v34, 0xffff0000, v34
	v_or_b32_sdwa v33, v35, v33 dst_sel:DWORD dst_unused:UNUSED_PAD src0_sel:DWORD src1_sel:WORD_1
	v_or_b32_sdwa v32, v34, v32 dst_sel:DWORD dst_unused:UNUSED_PAD src0_sel:DWORD src1_sel:WORD_1
	global_store_dwordx2 v[44:45], v[32:33], off offset:1536
	s_and_b64 exec, exec, s[0:1]
	s_cbranch_execz .LBB0_216
	v_cndmask_b32_e64 v32, v85, 16, s[2:3]
	v_mul_hi_i32_i24_e32 v33, 0x6000, v32
	v_mul_i32_i24_e32 v32, 0x6000, v32
	v_lshl_add_u64 v[34:35], s[12:13], 0, v[32:33]
	v_lshl_add_u64 v[32:33], v[34:35], 0, s[24:25]
	v_lshl_add_u64 v[40:41], v[32:33], 0, v[60:61]
	global_load_dwordx4 v[36:39], v[64:65], off
	v_lshl_add_u64 v[34:35], v[34:35], 0, v[60:61]
	global_load_dwordx4 v[40:43], v[40:41], off
	v_mov_b32_e32 v48, v28
	global_load_dwordx4 v[44:47], v[34:35], off
	global_load_dwordx4 v[120:123], v[64:65], off offset:1024
	v_mov_b32_e32 v156, v70
	v_mov_b32_e32 v157, v61
	v_lshl_add_u64 v[158:159], v[32:33], 0, v[156:157]
	global_load_dwordx4 v[124:127], v[158:159], off
	global_load_dwordx4 v[128:131], v[34:35], off offset:1024
	global_load_dwordx4 v[132:135], v[64:65], off offset:2048
	v_mov_b32_e32 v156, v74
	v_mov_b32_e32 v157, v61
	v_lshl_add_u64 v[158:159], v[32:33], 0, v[156:157]
	global_load_dwordx4 v[136:139], v[158:159], off
	global_load_dwordx4 v[140:143], v[34:35], off offset:2048
	global_load_dwordx4 v[144:147], v[64:65], off offset:3072
	v_mov_b32_e32 v156, v78
	v_mov_b32_e32 v157, v61
	v_lshl_add_u64 v[158:159], v[32:33], 0, v[156:157]
	global_load_dwordx4 v[148:151], v[158:159], off
	global_load_dwordx4 v[152:155], v[34:35], off offset:3072
	v_mov_b32_e32 v50, v28
	v_mov_b32_e32 v52, v29
	v_mov_b32_e32 v28, v29
	v_mov_b32_e32 v29, v25
	v_mov_b32_e32 v51, v24
	v_mov_b32_e32 v58, v21
	v_mov_b32_e32 v59, v13
	v_pk_mul_f32 v[28:29], v[28:29], v[28:29]
	v_mov_b32_e32 v54, v30
	v_mov_b32_e32 v55, v26
	v_mov_b32_e32 v56, v20
	v_mov_b32_e32 v57, v12
	v_pk_mul_f32 v[58:59], v[58:59], v[58:59]
	v_pk_fma_f32 v[28:29], v[50:51], v[50:51], v[28:29]
	v_mov_b32_e32 v49, v30
	v_mov_b32_e32 v53, v31
	v_mov_b32_e32 v30, v31
	v_mov_b32_e32 v31, v27
	v_mov_b32_e32 v86, v22
	v_mov_b32_e32 v87, v14
	v_pk_fma_f32 v[50:51], v[56:57], v[56:57], v[58:59]
	v_pk_fma_f32 v[28:29], v[54:55], v[54:55], v[28:29]
	v_mov_b32_e32 v90, v23
	v_mov_b32_e32 v91, v15
	v_pk_fma_f32 v[50:51], v[86:87], v[86:87], v[50:51]
	v_pk_fma_f32 v[28:29], v[30:31], v[30:31], v[28:29]
	v_pk_fma_f32 v[30:31], v[90:91], v[90:91], v[50:51]
	v_add_f32_e32 v28, v28, v29
	v_add_f32_e32 v28, v28, v30
	v_add_f32_e32 v28, v28, v31
	v_ashrrev_i32_e32 v85, 31, v84
	s_nop 0
	v_add_f32_dpp v28, v28, v28 quad_perm:[1,0,3,2] row_mask:0xf bank_mask:0xf bound_ctrl:1
	s_nop 1
	v_add_f32_dpp v28, v28, v28 quad_perm:[2,3,0,1] row_mask:0xf bank_mask:0xf bound_ctrl:1
	s_nop 1
	v_add_f32_dpp v28, v28, v28 row_half_mirror row_mask:0xf bank_mask:0xf bound_ctrl:1
	s_nop 1
	v_add_f32_dpp v28, v28, v28 row_mirror row_mask:0xf bank_mask:0xf bound_ctrl:1
	s_nop 0
	v_readlane_b32 s2, v28, 16
	v_readlane_b32 s3, v28, 48
	v_readlane_b32 s0, v28, 0
	v_readlane_b32 s1, v28, 32
	v_mov_b32_e32 v28, s2
	v_mov_b32_e32 v29, s3
	v_pk_add_f32 v[28:29], s[0:1], v[28:29]
	s_nop 0
	v_add_f32_e32 v28, v28, v29
	v_fmamk_f32 v28, v28, 0x3a800000, v88
	v_mul_f32_e32 v29, 0x4b800000, v28
	v_cmp_gt_f32_e64 s[0:1], s48, v28
	s_nop 1
	v_cndmask_b32_e64 v28, v28, v29, s[0:1]
	v_rsq_f32_e32 v30, v28
	v_lshlrev_b64 v[28:29], 11, v[84:85]
	v_lshl_add_u64 v[50:51], v[66:67], 0, v[28:29]
	v_mul_f32_e32 v28, 0x45800000, v30
	v_cndmask_b32_e64 v54, v30, v28, s[0:1]
	v_pk_mul_f32 v[28:29], v[48:49], v[54:55] op_sel_hi:[1,0]
	v_pk_mul_f32 v[30:31], v[52:53], v[54:55] op_sel_hi:[1,0]
	v_cmp_gt_i32_e64 s[0:1], s41, v83
	s_waitcnt vmcnt(0) lgkmcnt(0)
	v_mov_b32_e32 v49, v38
	v_mov_b32_e32 v38, v37
	v_mov_b32_e32 v37, v42
	v_mov_b32_e32 v42, v41
	v_mov_b32_e32 v48, v36
	v_pk_mul_f32 v[30:31], v[38:39], v[30:31]
	v_mov_b32_e32 v36, v40
	v_mov_b32_e32 v39, v46
	v_mov_b32_e32 v46, v45
	v_pk_add_f32 v[40:41], v[42:43], 1.0 op_sel_hi:[1,0]
	v_pk_mul_f32 v[28:29], v[48:49], v[28:29]
	v_mov_b32_e32 v38, v44
	v_pk_add_f32 v[36:37], v[36:37], 1.0 op_sel_hi:[1,0]
	v_pk_fma_f32 v[30:31], v[40:41], v[30:31], v[46:47]
	v_pk_fma_f32 v[28:29], v[36:37], v[28:29], v[38:39]
	v_and_b32_sdwa v38, v31, v89 dst_sel:DWORD dst_unused:UNUSED_PAD src0_sel:WORD_1 src1_sel:DWORD
	v_and_b32_sdwa v39, v30, v89 dst_sel:DWORD dst_unused:UNUSED_PAD src0_sel:WORD_1 src1_sel:DWORD
	v_and_b32_sdwa v36, v29, v89 dst_sel:DWORD dst_unused:UNUSED_PAD src0_sel:WORD_1 src1_sel:DWORD
	v_and_b32_sdwa v37, v28, v89 dst_sel:DWORD dst_unused:UNUSED_PAD src0_sel:WORD_1 src1_sel:DWORD
	v_add3_u32 v31, v31, v38, s49
	v_add3_u32 v30, v30, v39, s49
	v_add3_u32 v28, v28, v37, s49
	v_add3_u32 v29, v29, v36, s49
	v_and_b32_e32 v31, 0xffff0000, v31
	v_and_b32_e32 v30, 0xffff0000, v30
	v_or_b32_sdwa v29, v31, v29 dst_sel:DWORD dst_unused:UNUSED_PAD src0_sel:DWORD src1_sel:WORD_1
	v_or_b32_sdwa v28, v30, v28 dst_sel:DWORD dst_unused:UNUSED_PAD src0_sel:DWORD src1_sel:WORD_1
	global_store_dwordx2 v[50:51], v[28:29], off
	v_lshl_add_u64 v[36:37], v[32:33], 0, v[70:71]
	s_nop 0
	v_mov_b32_e32 v44, v24
	v_mov_b32_e32 v45, v26
	v_mov_b32_e32 v26, v25
	v_pk_mul_f32 v[24:25], v[44:45], v[54:55] op_sel_hi:[1,0]
	v_pk_mul_f32 v[26:27], v[26:27], v[54:55] op_sel_hi:[1,0]
	s_waitcnt lgkmcnt(0)
	v_mov_b32_e32 v28, v120
	v_mov_b32_e32 v29, v121
	v_mov_b32_e32 v30, v122
	v_mov_b32_e32 v31, v123
	v_mov_b32_e32 v36, v124
	v_mov_b32_e32 v37, v125
	v_mov_b32_e32 v38, v126
	v_mov_b32_e32 v39, v127
	v_mov_b32_e32 v40, v128
	v_mov_b32_e32 v41, v129
	v_mov_b32_e32 v42, v130
	v_mov_b32_e32 v43, v131
	v_mov_b32_e32 v45, v30
	v_mov_b32_e32 v47, v38
	v_mov_b32_e32 v30, v29
	v_mov_b32_e32 v38, v37
	v_mov_b32_e32 v44, v28
	v_mov_b32_e32 v46, v36
	v_mov_b32_e32 v49, v42
	v_mov_b32_e32 v42, v41
	v_pk_mul_f32 v[26:27], v[26:27], v[30:31]
	v_pk_add_f32 v[30:31], v[38:39], 1.0 op_sel_hi:[1,0]
	v_mov_b32_e32 v48, v40
	v_pk_mul_f32 v[24:25], v[24:25], v[44:45]
	v_pk_add_f32 v[28:29], v[46:47], 1.0 op_sel_hi:[1,0]
	v_pk_fma_f32 v[26:27], v[26:27], v[30:31], v[42:43]
	v_pk_fma_f32 v[24:25], v[24:25], v[28:29], v[48:49]
	v_and_b32_sdwa v30, v27, v89 dst_sel:DWORD dst_unused:UNUSED_PAD src0_sel:WORD_1 src1_sel:DWORD
	v_and_b32_sdwa v31, v26, v89 dst_sel:DWORD dst_unused:UNUSED_PAD src0_sel:WORD_1 src1_sel:DWORD
	v_and_b32_sdwa v28, v25, v89 dst_sel:DWORD dst_unused:UNUSED_PAD src0_sel:WORD_1 src1_sel:DWORD
	v_and_b32_sdwa v29, v24, v89 dst_sel:DWORD dst_unused:UNUSED_PAD src0_sel:WORD_1 src1_sel:DWORD
	v_add3_u32 v27, v27, v30, s49
	v_add3_u32 v26, v26, v31, s49
	v_add3_u32 v24, v24, v29, s49
	v_add3_u32 v25, v25, v28, s49
	v_and_b32_e32 v27, 0xffff0000, v27
	v_and_b32_e32 v26, 0xffff0000, v26
	v_or_b32_sdwa v25, v27, v25 dst_sel:DWORD dst_unused:UNUSED_PAD src0_sel:DWORD src1_sel:WORD_1
	v_or_b32_sdwa v24, v26, v24 dst_sel:DWORD dst_unused:UNUSED_PAD src0_sel:DWORD src1_sel:WORD_1
	global_store_dwordx2 v[50:51], v[24:25], off offset:512
	v_lshl_add_u64 v[28:29], v[32:33], 0, v[74:75]
	s_nop 0
	v_mov_b32_e32 v40, v20
	v_mov_b32_e32 v41, v22
	v_mov_b32_e32 v22, v21
	v_pk_mul_f32 v[20:21], v[40:41], v[54:55] op_sel_hi:[1,0]
	v_pk_mul_f32 v[22:23], v[22:23], v[54:55] op_sel_hi:[1,0]
	s_waitcnt lgkmcnt(0)
	v_mov_b32_e32 v24, v132
	v_mov_b32_e32 v25, v133
	v_mov_b32_e32 v26, v134
	v_mov_b32_e32 v27, v135
	v_mov_b32_e32 v28, v136
	v_mov_b32_e32 v29, v137
	v_mov_b32_e32 v30, v138
	v_mov_b32_e32 v31, v139
	v_mov_b32_e32 v36, v140
	v_mov_b32_e32 v37, v141
	v_mov_b32_e32 v38, v142
	v_mov_b32_e32 v39, v143
	v_mov_b32_e32 v41, v26
	v_mov_b32_e32 v43, v30
	v_mov_b32_e32 v26, v25
	v_mov_b32_e32 v30, v29
	v_mov_b32_e32 v40, v24
	v_mov_b32_e32 v42, v28
	v_mov_b32_e32 v45, v38
	v_mov_b32_e32 v38, v37
	v_pk_mul_f32 v[22:23], v[22:23], v[26:27]
	v_pk_add_f32 v[26:27], v[30:31], 1.0 op_sel_hi:[1,0]
	v_mov_b32_e32 v44, v36
	v_pk_mul_f32 v[20:21], v[20:21], v[40:41]
	v_pk_add_f32 v[24:25], v[42:43], 1.0 op_sel_hi:[1,0]
	v_pk_fma_f32 v[22:23], v[22:23], v[26:27], v[38:39]
	v_pk_fma_f32 v[20:21], v[20:21], v[24:25], v[44:45]
	v_and_b32_sdwa v26, v23, v89 dst_sel:DWORD dst_unused:UNUSED_PAD src0_sel:WORD_1 src1_sel:DWORD
	v_and_b32_sdwa v27, v22, v89 dst_sel:DWORD dst_unused:UNUSED_PAD src0_sel:WORD_1 src1_sel:DWORD
	v_and_b32_sdwa v24, v21, v89 dst_sel:DWORD dst_unused:UNUSED_PAD src0_sel:WORD_1 src1_sel:DWORD
	v_and_b32_sdwa v25, v20, v89 dst_sel:DWORD dst_unused:UNUSED_PAD src0_sel:WORD_1 src1_sel:DWORD
	v_add3_u32 v23, v23, v26, s49
	v_add3_u32 v22, v22, v27, s49
	v_add3_u32 v20, v20, v25, s49
	v_add3_u32 v21, v21, v24, s49
	v_and_b32_e32 v23, 0xffff0000, v23
	v_and_b32_e32 v22, 0xffff0000, v22
	v_or_b32_sdwa v21, v23, v21 dst_sel:DWORD dst_unused:UNUSED_PAD src0_sel:DWORD src1_sel:WORD_1
	v_or_b32_sdwa v20, v22, v20 dst_sel:DWORD dst_unused:UNUSED_PAD src0_sel:DWORD src1_sel:WORD_1
	global_store_dwordx2 v[50:51], v[20:21], off offset:1024
	v_lshl_add_u64 v[24:25], v[32:33], 0, v[78:79]
	s_nop 0
	v_mov_b32_e32 v32, v12
	v_mov_b32_e32 v33, v14
	v_mov_b32_e32 v14, v13
	v_pk_mul_f32 v[12:13], v[32:33], v[54:55] op_sel_hi:[1,0]
	v_pk_mul_f32 v[14:15], v[14:15], v[54:55] op_sel_hi:[1,0]
	s_waitcnt lgkmcnt(0)
	v_mov_b32_e32 v20, v144
	v_mov_b32_e32 v21, v145
	v_mov_b32_e32 v22, v146
	v_mov_b32_e32 v23, v147
	v_mov_b32_e32 v24, v148
	v_mov_b32_e32 v25, v149
	v_mov_b32_e32 v26, v150
	v_mov_b32_e32 v27, v151
	v_mov_b32_e32 v28, v152
	v_mov_b32_e32 v29, v153
	v_mov_b32_e32 v30, v154
	v_mov_b32_e32 v31, v155
	v_mov_b32_e32 v33, v22
	v_mov_b32_e32 v35, v26
	v_mov_b32_e32 v22, v21
	v_mov_b32_e32 v26, v25
	v_mov_b32_e32 v32, v20
	v_mov_b32_e32 v34, v24
	v_mov_b32_e32 v37, v30
	v_mov_b32_e32 v30, v29
	v_pk_mul_f32 v[14:15], v[14:15], v[22:23]
	v_pk_add_f32 v[22:23], v[26:27], 1.0 op_sel_hi:[1,0]
	v_mov_b32_e32 v36, v28
	v_pk_mul_f32 v[12:13], v[12:13], v[32:33]
	v_pk_add_f32 v[20:21], v[34:35], 1.0 op_sel_hi:[1,0]
	v_pk_fma_f32 v[14:15], v[14:15], v[22:23], v[30:31]
	v_pk_fma_f32 v[12:13], v[12:13], v[20:21], v[36:37]
	v_and_b32_sdwa v22, v15, v89 dst_sel:DWORD dst_unused:UNUSED_PAD src0_sel:WORD_1 src1_sel:DWORD
	v_and_b32_sdwa v23, v14, v89 dst_sel:DWORD dst_unused:UNUSED_PAD src0_sel:WORD_1 src1_sel:DWORD
	v_and_b32_sdwa v20, v13, v89 dst_sel:DWORD dst_unused:UNUSED_PAD src0_sel:WORD_1 src1_sel:DWORD
	v_and_b32_sdwa v21, v12, v89 dst_sel:DWORD dst_unused:UNUSED_PAD src0_sel:WORD_1 src1_sel:DWORD
	v_add3_u32 v15, v15, v22, s49
	v_add3_u32 v14, v14, v23, s49
	v_add3_u32 v12, v12, v21, s49
	v_add3_u32 v13, v13, v20, s49
	v_and_b32_e32 v15, 0xffff0000, v15
	v_and_b32_e32 v14, 0xffff0000, v14
	v_or_b32_sdwa v13, v15, v13 dst_sel:DWORD dst_unused:UNUSED_PAD src0_sel:DWORD src1_sel:WORD_1
	v_or_b32_sdwa v12, v14, v12 dst_sel:DWORD dst_unused:UNUSED_PAD src0_sel:DWORD src1_sel:WORD_1
	global_store_dwordx2 v[50:51], v[12:13], off offset:1536
	s_and_b64 exec, exec, s[0:1]
	s_cbranch_execz .LBB0_216
	v_cndmask_b32_e64 v12, v63, 16, vcc
	v_mul_hi_i32_i24_e32 v13, 0x6000, v12
	v_mul_i32_i24_e32 v12, 0x6000, v12
	v_lshl_add_u64 v[14:15], s[12:13], 0, v[12:13]
	v_lshl_add_u64 v[12:13], v[14:15], 0, s[24:25]
	global_load_dwordx4 v[20:23], v[64:65], off
	v_lshl_add_u64 v[24:25], v[12:13], 0, v[60:61]
	global_load_dwordx4 v[24:27], v[24:25], off
	v_lshl_add_u64 v[14:15], v[14:15], 0, v[60:61]
	global_load_dwordx4 v[28:31], v[14:15], off
	global_load_dwordx4 v[120:123], v[64:65], off offset:1024
	v_mov_b32_e32 v156, v70
	v_mov_b32_e32 v157, v61
	v_lshl_add_u64 v[158:159], v[12:13], 0, v[156:157]
	global_load_dwordx4 v[124:127], v[158:159], off
	global_load_dwordx4 v[128:131], v[14:15], off offset:1024
	global_load_dwordx4 v[132:135], v[64:65], off offset:2048
	v_mov_b32_e32 v156, v74
	v_mov_b32_e32 v157, v61
	v_lshl_add_u64 v[158:159], v[12:13], 0, v[156:157]
	global_load_dwordx4 v[136:139], v[158:159], off
	global_load_dwordx4 v[140:143], v[14:15], off offset:2048
	global_load_dwordx4 v[144:147], v[64:65], off offset:3072
	v_mov_b32_e32 v156, v78
	v_mov_b32_e32 v157, v61
	v_lshl_add_u64 v[158:159], v[12:13], 0, v[156:157]
	global_load_dwordx4 v[148:151], v[158:159], off
	global_load_dwordx4 v[152:155], v[14:15], off offset:3072
	v_mov_b32_e32 v32, v16
	v_mov_b32_e32 v34, v16
	v_mov_b32_e32 v36, v17
	v_mov_b32_e32 v16, v17
	v_mov_b32_e32 v17, v9
	v_mov_b32_e32 v35, v8
	v_mov_b32_e32 v42, v5
	v_mov_b32_e32 v43, v1
	v_pk_mul_f32 v[16:17], v[16:17], v[16:17]
	v_mov_b32_e32 v38, v18
	v_mov_b32_e32 v39, v10
	v_mov_b32_e32 v40, v4
	v_mov_b32_e32 v41, v0
	v_pk_mul_f32 v[42:43], v[42:43], v[42:43]
	v_pk_fma_f32 v[16:17], v[34:35], v[34:35], v[16:17]
	v_mov_b32_e32 v33, v18
	v_mov_b32_e32 v37, v19
	v_mov_b32_e32 v18, v19
	v_mov_b32_e32 v19, v11
	v_mov_b32_e32 v44, v6
	v_mov_b32_e32 v45, v2
	v_pk_fma_f32 v[34:35], v[40:41], v[40:41], v[42:43]
	v_pk_fma_f32 v[16:17], v[38:39], v[38:39], v[16:17]
	v_mov_b32_e32 v46, v7
	v_mov_b32_e32 v47, v3
	v_pk_fma_f32 v[34:35], v[44:45], v[44:45], v[34:35]
	v_pk_fma_f32 v[16:17], v[18:19], v[18:19], v[16:17]
	v_pk_fma_f32 v[18:19], v[46:47], v[46:47], v[34:35]
	v_add_f32_e32 v16, v16, v17
	v_add_f32_e32 v16, v16, v18
	v_add_f32_e32 v16, v16, v19
	v_ashrrev_i32_e32 v83, 31, v82
	v_mov_b32_e32 v71, v61
	v_add_f32_dpp v16, v16, v16 quad_perm:[1,0,3,2] row_mask:0xf bank_mask:0xf bound_ctrl:1
	v_mov_b32_e32 v75, v61
	v_mov_b32_e32 v79, v61
	v_add_f32_dpp v16, v16, v16 quad_perm:[2,3,0,1] row_mask:0xf bank_mask:0xf bound_ctrl:1
	s_nop 1
	v_add_f32_dpp v16, v16, v16 row_half_mirror row_mask:0xf bank_mask:0xf bound_ctrl:1
	s_nop 1
	v_add_f32_dpp v16, v16, v16 row_mirror row_mask:0xf bank_mask:0xf bound_ctrl:1
	s_nop 0
	v_readlane_b32 s2, v16, 16
	v_readlane_b32 s3, v16, 48
	v_readlane_b32 s0, v16, 0
	v_readlane_b32 s1, v16, 32
	v_mov_b32_e32 v16, s2
	v_mov_b32_e32 v17, s3
	v_pk_add_f32 v[16:17], s[0:1], v[16:17]
	s_nop 0
	v_add_f32_e32 v16, v16, v17
	v_fmamk_f32 v16, v16, 0x3a800000, v88
	v_mul_f32_e32 v17, 0x4b800000, v16
	v_cmp_gt_f32_e32 vcc, s48, v16
	s_nop 1
	v_cndmask_b32_e32 v16, v16, v17, vcc
	v_rsq_f32_e32 v18, v16
	v_lshlrev_b64 v[16:17], 11, v[82:83]
	v_lshl_add_u64 v[16:17], v[66:67], 0, v[16:17]
	v_mul_f32_e32 v19, 0x45800000, v18
	v_cndmask_b32_e32 v34, v18, v19, vcc
	v_pk_mul_f32 v[18:19], v[32:33], v[34:35] op_sel_hi:[1,0]
	v_pk_mul_f32 v[32:33], v[36:37], v[34:35] op_sel_hi:[1,0]
	s_waitcnt vmcnt(0) lgkmcnt(0)
	v_mov_b32_e32 v37, v22
	v_mov_b32_e32 v22, v21
	v_mov_b32_e32 v36, v20
	v_pk_mul_f32 v[20:21], v[22:23], v[32:33]
	v_mov_b32_e32 v23, v26
	v_mov_b32_e32 v26, v25
	v_mov_b32_e32 v22, v24
	v_mov_b32_e32 v33, v30
	v_mov_b32_e32 v30, v29
	v_pk_add_f32 v[24:25], v[26:27], 1.0 op_sel_hi:[1,0]
	v_pk_mul_f32 v[18:19], v[36:37], v[18:19]
	v_mov_b32_e32 v32, v28
	v_pk_add_f32 v[22:23], v[22:23], 1.0 op_sel_hi:[1,0]
	v_pk_fma_f32 v[20:21], v[24:25], v[20:21], v[30:31]
	v_pk_fma_f32 v[18:19], v[22:23], v[18:19], v[32:33]
	v_and_b32_sdwa v24, v21, v89 dst_sel:DWORD dst_unused:UNUSED_PAD src0_sel:WORD_1 src1_sel:DWORD
	v_and_b32_sdwa v25, v20, v89 dst_sel:DWORD dst_unused:UNUSED_PAD src0_sel:WORD_1 src1_sel:DWORD
	v_and_b32_sdwa v22, v19, v89 dst_sel:DWORD dst_unused:UNUSED_PAD src0_sel:WORD_1 src1_sel:DWORD
	v_and_b32_sdwa v23, v18, v89 dst_sel:DWORD dst_unused:UNUSED_PAD src0_sel:WORD_1 src1_sel:DWORD
	v_add3_u32 v21, v21, v24, s49
	v_add3_u32 v20, v20, v25, s49
	v_add3_u32 v18, v18, v23, s49
	v_add3_u32 v19, v19, v22, s49
	v_and_b32_e32 v21, 0xffff0000, v21
	v_and_b32_e32 v20, 0xffff0000, v20
	v_or_b32_sdwa v19, v21, v19 dst_sel:DWORD dst_unused:UNUSED_PAD src0_sel:DWORD src1_sel:WORD_1
	v_or_b32_sdwa v18, v20, v18 dst_sel:DWORD dst_unused:UNUSED_PAD src0_sel:DWORD src1_sel:WORD_1
	global_store_dwordx2 v[16:17], v[18:19], off
	v_lshl_add_u64 v[22:23], v[12:13], 0, v[70:71]
	s_nop 0
	v_mov_b32_e32 v30, v8
	v_mov_b32_e32 v31, v10
	v_mov_b32_e32 v10, v9
	v_pk_mul_f32 v[8:9], v[30:31], v[34:35] op_sel_hi:[1,0]
	v_pk_mul_f32 v[10:11], v[10:11], v[34:35] op_sel_hi:[1,0]
	s_waitcnt lgkmcnt(0)
	v_mov_b32_e32 v18, v120
	v_mov_b32_e32 v19, v121
	v_mov_b32_e32 v20, v122
	v_mov_b32_e32 v21, v123
	v_mov_b32_e32 v22, v124
	v_mov_b32_e32 v23, v125
	v_mov_b32_e32 v24, v126
	v_mov_b32_e32 v25, v127
	v_mov_b32_e32 v26, v128
	v_mov_b32_e32 v27, v129
	v_mov_b32_e32 v28, v130
	v_mov_b32_e32 v29, v131
	v_mov_b32_e32 v31, v20
	v_mov_b32_e32 v33, v24
	v_mov_b32_e32 v20, v19
	v_mov_b32_e32 v24, v23
	v_mov_b32_e32 v30, v18
	v_mov_b32_e32 v32, v22
	v_mov_b32_e32 v37, v28
	v_mov_b32_e32 v28, v27
	v_pk_mul_f32 v[10:11], v[10:11], v[20:21]
	v_pk_add_f32 v[20:21], v[24:25], 1.0 op_sel_hi:[1,0]
	v_mov_b32_e32 v36, v26
	v_pk_mul_f32 v[8:9], v[8:9], v[30:31]
	v_pk_add_f32 v[18:19], v[32:33], 1.0 op_sel_hi:[1,0]
	v_pk_fma_f32 v[10:11], v[10:11], v[20:21], v[28:29]
	v_pk_fma_f32 v[8:9], v[8:9], v[18:19], v[36:37]
	v_and_b32_sdwa v20, v11, v89 dst_sel:DWORD dst_unused:UNUSED_PAD src0_sel:WORD_1 src1_sel:DWORD
	v_and_b32_sdwa v21, v10, v89 dst_sel:DWORD dst_unused:UNUSED_PAD src0_sel:WORD_1 src1_sel:DWORD
	v_and_b32_sdwa v18, v9, v89 dst_sel:DWORD dst_unused:UNUSED_PAD src0_sel:WORD_1 src1_sel:DWORD
	v_and_b32_sdwa v19, v8, v89 dst_sel:DWORD dst_unused:UNUSED_PAD src0_sel:WORD_1 src1_sel:DWORD
	v_add3_u32 v11, v11, v20, s49
	v_add3_u32 v10, v10, v21, s49
	v_add3_u32 v8, v8, v19, s49
	v_add3_u32 v9, v9, v18, s49
	v_and_b32_e32 v11, 0xffff0000, v11
	v_and_b32_e32 v10, 0xffff0000, v10
	v_or_b32_sdwa v9, v11, v9 dst_sel:DWORD dst_unused:UNUSED_PAD src0_sel:DWORD src1_sel:WORD_1
	v_or_b32_sdwa v8, v10, v8 dst_sel:DWORD dst_unused:UNUSED_PAD src0_sel:DWORD src1_sel:WORD_1
	global_store_dwordx2 v[16:17], v[8:9], off offset:512
	v_lshl_add_u64 v[18:19], v[12:13], 0, v[74:75]
	s_nop 0
	v_mov_b32_e32 v26, v4
	v_mov_b32_e32 v27, v6
	v_mov_b32_e32 v6, v5
	v_pk_mul_f32 v[4:5], v[26:27], v[34:35] op_sel_hi:[1,0]
	v_pk_mul_f32 v[6:7], v[6:7], v[34:35] op_sel_hi:[1,0]
	s_waitcnt lgkmcnt(0)
	v_mov_b32_e32 v8, v132
	v_mov_b32_e32 v9, v133
	v_mov_b32_e32 v10, v134
	v_mov_b32_e32 v11, v135
	v_mov_b32_e32 v18, v136
	v_mov_b32_e32 v19, v137
	v_mov_b32_e32 v20, v138
	v_mov_b32_e32 v21, v139
	v_mov_b32_e32 v22, v140
	v_mov_b32_e32 v23, v141
	v_mov_b32_e32 v24, v142
	v_mov_b32_e32 v25, v143
	v_mov_b32_e32 v27, v10
	v_mov_b32_e32 v29, v20
	v_mov_b32_e32 v10, v9
	v_mov_b32_e32 v20, v19
	v_mov_b32_e32 v26, v8
	v_mov_b32_e32 v28, v18
	v_mov_b32_e32 v31, v24
	v_mov_b32_e32 v24, v23
	v_pk_mul_f32 v[6:7], v[6:7], v[10:11]
	v_pk_add_f32 v[10:11], v[20:21], 1.0 op_sel_hi:[1,0]
	v_mov_b32_e32 v30, v22
	v_pk_mul_f32 v[4:5], v[4:5], v[26:27]
	v_pk_add_f32 v[8:9], v[28:29], 1.0 op_sel_hi:[1,0]
	v_pk_fma_f32 v[6:7], v[6:7], v[10:11], v[24:25]
	v_pk_fma_f32 v[4:5], v[4:5], v[8:9], v[30:31]
	v_and_b32_sdwa v10, v7, v89 dst_sel:DWORD dst_unused:UNUSED_PAD src0_sel:WORD_1 src1_sel:DWORD
	v_and_b32_sdwa v11, v6, v89 dst_sel:DWORD dst_unused:UNUSED_PAD src0_sel:WORD_1 src1_sel:DWORD
	v_and_b32_sdwa v8, v5, v89 dst_sel:DWORD dst_unused:UNUSED_PAD src0_sel:WORD_1 src1_sel:DWORD
	v_and_b32_sdwa v9, v4, v89 dst_sel:DWORD dst_unused:UNUSED_PAD src0_sel:WORD_1 src1_sel:DWORD
	v_add3_u32 v7, v7, v10, s49
	v_add3_u32 v6, v6, v11, s49
	v_add3_u32 v4, v4, v9, s49
	v_add3_u32 v5, v5, v8, s49
	v_and_b32_e32 v7, 0xffff0000, v7
	v_and_b32_e32 v6, 0xffff0000, v6
	v_or_b32_sdwa v5, v7, v5 dst_sel:DWORD dst_unused:UNUSED_PAD src0_sel:DWORD src1_sel:WORD_1
	v_or_b32_sdwa v4, v6, v4 dst_sel:DWORD dst_unused:UNUSED_PAD src0_sel:DWORD src1_sel:WORD_1
	global_store_dwordx2 v[16:17], v[4:5], off offset:1024
	v_lshl_add_u64 v[8:9], v[12:13], 0, v[78:79]
	s_nop 0
	v_mov_b32_e32 v18, v0
	v_mov_b32_e32 v19, v2
	v_mov_b32_e32 v2, v1
	v_pk_mul_f32 v[0:1], v[18:19], v[34:35] op_sel_hi:[1,0]
	v_pk_mul_f32 v[2:3], v[2:3], v[34:35] op_sel_hi:[1,0]
	s_waitcnt lgkmcnt(0)
	v_mov_b32_e32 v4, v144
	v_mov_b32_e32 v5, v145
	v_mov_b32_e32 v6, v146
	v_mov_b32_e32 v7, v147
	v_mov_b32_e32 v8, v148
	v_mov_b32_e32 v9, v149
	v_mov_b32_e32 v10, v150
	v_mov_b32_e32 v11, v151
	v_mov_b32_e32 v12, v152
	v_mov_b32_e32 v13, v153
	v_mov_b32_e32 v14, v154
	v_mov_b32_e32 v15, v155
	v_mov_b32_e32 v19, v6
	v_mov_b32_e32 v21, v10
	v_mov_b32_e32 v6, v5
	v_mov_b32_e32 v10, v9
	v_mov_b32_e32 v18, v4
	v_mov_b32_e32 v20, v8
	v_mov_b32_e32 v23, v14
	v_mov_b32_e32 v14, v13
	v_pk_mul_f32 v[2:3], v[2:3], v[6:7]
	v_pk_add_f32 v[6:7], v[10:11], 1.0 op_sel_hi:[1,0]
	v_mov_b32_e32 v22, v12
	v_pk_mul_f32 v[0:1], v[0:1], v[18:19]
	v_pk_add_f32 v[4:5], v[20:21], 1.0 op_sel_hi:[1,0]
	v_pk_fma_f32 v[2:3], v[2:3], v[6:7], v[14:15]
	v_pk_fma_f32 v[0:1], v[0:1], v[4:5], v[22:23]
	v_and_b32_sdwa v6, v3, v89 dst_sel:DWORD dst_unused:UNUSED_PAD src0_sel:WORD_1 src1_sel:DWORD
	v_and_b32_sdwa v7, v2, v89 dst_sel:DWORD dst_unused:UNUSED_PAD src0_sel:WORD_1 src1_sel:DWORD
	v_and_b32_sdwa v4, v1, v89 dst_sel:DWORD dst_unused:UNUSED_PAD src0_sel:WORD_1 src1_sel:DWORD
	v_and_b32_sdwa v5, v0, v89 dst_sel:DWORD dst_unused:UNUSED_PAD src0_sel:WORD_1 src1_sel:DWORD
	v_add3_u32 v3, v3, v6, s49
	v_add3_u32 v2, v2, v7, s49
	v_add3_u32 v0, v0, v5, s49
	v_add3_u32 v1, v1, v4, s49
	v_and_b32_e32 v3, 0xffff0000, v3
	v_and_b32_e32 v2, 0xffff0000, v2
	v_or_b32_sdwa v1, v3, v1 dst_sel:DWORD dst_unused:UNUSED_PAD src0_sel:DWORD src1_sel:WORD_1
	v_or_b32_sdwa v0, v2, v0 dst_sel:DWORD dst_unused:UNUSED_PAD src0_sel:DWORD src1_sel:WORD_1
	global_store_dwordx2 v[16:17], v[0:1], off offset:1536
	s_branch .LBB0_216
